# v53: adaLN GEMV k loop with 64 weight loads in flight (two round trips per item instead of four)
# baseline (speedup 1.0000x reference)
.LBB0_6:
	v_lshl_add_u64 v[40:41], v[8:9], 0, s[28:29]
	global_load_dword v56, v[40:41], off
	s_add_u32 s28, s28, 0x3000
	s_addc_u32 s29, s29, 0
	v_lshl_add_u64 v[40:41], v[8:9], 0, s[28:29]
	global_load_dword v57, v[40:41], off
	s_add_u32 s28, s28, 0x3000
	s_addc_u32 s29, s29, 0
	v_lshl_add_u64 v[40:41], v[8:9], 0, s[28:29]
	global_load_dword v58, v[40:41], off
	s_add_u32 s28, s28, 0x3000
	s_addc_u32 s29, s29, 0
	v_lshl_add_u64 v[40:41], v[8:9], 0, s[28:29]
	global_load_dword v59, v[40:41], off
	s_add_u32 s28, s28, 0x3000
	s_addc_u32 s29, s29, 0
	v_lshl_add_u64 v[40:41], v[8:9], 0, s[28:29]
	global_load_dword v60, v[40:41], off
	s_add_u32 s28, s28, 0x3000
	s_addc_u32 s29, s29, 0
	v_lshl_add_u64 v[40:41], v[8:9], 0, s[28:29]
	global_load_dword v61, v[40:41], off
	s_add_u32 s28, s28, 0x3000
	s_addc_u32 s29, s29, 0
	v_lshl_add_u64 v[40:41], v[8:9], 0, s[28:29]
	global_load_dword v62, v[40:41], off
	s_add_u32 s28, s28, 0x3000
	s_addc_u32 s29, s29, 0
	v_lshl_add_u64 v[40:41], v[8:9], 0, s[28:29]
	global_load_dword v63, v[40:41], off
	s_add_u32 s28, s28, 0x3000
	s_addc_u32 s29, s29, 0
	v_lshl_add_u64 v[40:41], v[8:9], 0, s[28:29]
	global_load_dword v64, v[40:41], off
	s_add_u32 s28, s28, 0x3000
	s_addc_u32 s29, s29, 0
	v_lshl_add_u64 v[40:41], v[8:9], 0, s[28:29]
	global_load_dword v65, v[40:41], off
	s_add_u32 s28, s28, 0x3000
	s_addc_u32 s29, s29, 0
	v_lshl_add_u64 v[40:41], v[8:9], 0, s[28:29]
	global_load_dword v66, v[40:41], off
	s_add_u32 s28, s28, 0x3000
	s_addc_u32 s29, s29, 0
	v_lshl_add_u64 v[40:41], v[8:9], 0, s[28:29]
	global_load_dword v67, v[40:41], off
	s_add_u32 s28, s28, 0x3000
	s_addc_u32 s29, s29, 0
	v_lshl_add_u64 v[40:41], v[8:9], 0, s[28:29]
	global_load_dword v68, v[40:41], off
	s_add_u32 s28, s28, 0x3000
	s_addc_u32 s29, s29, 0
	v_lshl_add_u64 v[40:41], v[8:9], 0, s[28:29]
	global_load_dword v69, v[40:41], off
	s_add_u32 s28, s28, 0x3000
	s_addc_u32 s29, s29, 0
	v_lshl_add_u64 v[40:41], v[8:9], 0, s[28:29]
	global_load_dword v70, v[40:41], off
	s_add_u32 s28, s28, 0x3000
	s_addc_u32 s29, s29, 0
	v_lshl_add_u64 v[40:41], v[8:9], 0, s[28:29]
	global_load_dword v71, v[40:41], off
	s_add_u32 s28, s28, 0x3000
	s_addc_u32 s29, s29, 0
	v_lshl_add_u64 v[40:41], v[8:9], 0, s[28:29]
	global_load_dword v72, v[40:41], off
	s_add_u32 s28, s28, 0x3000
	s_addc_u32 s29, s29, 0
	v_lshl_add_u64 v[40:41], v[8:9], 0, s[28:29]
	global_load_dword v73, v[40:41], off
	s_add_u32 s28, s28, 0x3000
	s_addc_u32 s29, s29, 0
	v_lshl_add_u64 v[40:41], v[8:9], 0, s[28:29]
	global_load_dword v74, v[40:41], off
	s_add_u32 s28, s28, 0x3000
	s_addc_u32 s29, s29, 0
	v_lshl_add_u64 v[40:41], v[8:9], 0, s[28:29]
	global_load_dword v75, v[40:41], off
	s_add_u32 s28, s28, 0x3000
	s_addc_u32 s29, s29, 0
	v_lshl_add_u64 v[40:41], v[8:9], 0, s[28:29]
	global_load_dword v76, v[40:41], off
	s_add_u32 s28, s28, 0x3000
	s_addc_u32 s29, s29, 0
	v_lshl_add_u64 v[40:41], v[8:9], 0, s[28:29]
	global_load_dword v77, v[40:41], off
	s_add_u32 s28, s28, 0x3000
	s_addc_u32 s29, s29, 0
	v_lshl_add_u64 v[40:41], v[8:9], 0, s[28:29]
	global_load_dword v78, v[40:41], off
	s_add_u32 s28, s28, 0x3000
	s_addc_u32 s29, s29, 0
	v_lshl_add_u64 v[40:41], v[8:9], 0, s[28:29]
	global_load_dword v79, v[40:41], off
	s_add_u32 s28, s28, 0x3000
	s_addc_u32 s29, s29, 0
	v_lshl_add_u64 v[40:41], v[8:9], 0, s[28:29]
	global_load_dword v80, v[40:41], off
	s_add_u32 s28, s28, 0x3000
	s_addc_u32 s29, s29, 0
	v_lshl_add_u64 v[40:41], v[8:9], 0, s[28:29]
	global_load_dword v81, v[40:41], off
	s_add_u32 s28, s28, 0x3000
	s_addc_u32 s29, s29, 0
	v_lshl_add_u64 v[40:41], v[8:9], 0, s[28:29]
	global_load_dword v82, v[40:41], off
	s_add_u32 s28, s28, 0x3000
	s_addc_u32 s29, s29, 0
	v_lshl_add_u64 v[40:41], v[8:9], 0, s[28:29]
	global_load_dword v83, v[40:41], off
	s_add_u32 s28, s28, 0x3000
	s_addc_u32 s29, s29, 0
	v_lshl_add_u64 v[40:41], v[8:9], 0, s[28:29]
	global_load_dword v84, v[40:41], off
	s_add_u32 s28, s28, 0x3000
	s_addc_u32 s29, s29, 0
	v_lshl_add_u64 v[40:41], v[8:9], 0, s[28:29]
	global_load_dword v85, v[40:41], off
	s_add_u32 s28, s28, 0x3000
	s_addc_u32 s29, s29, 0
	v_lshl_add_u64 v[40:41], v[8:9], 0, s[28:29]
	global_load_dword v86, v[40:41], off
	s_add_u32 s28, s28, 0x3000
	s_addc_u32 s29, s29, 0
	v_lshl_add_u64 v[40:41], v[8:9], 0, s[28:29]
	global_load_dword v87, v[40:41], off
	s_add_u32 s28, s28, 0x3000
	s_addc_u32 s29, s29, 0
	v_lshl_add_u64 v[40:41], v[8:9], 0, s[28:29]
	global_load_dword v88, v[40:41], off
	s_add_u32 s28, s28, 0x3000
	s_addc_u32 s29, s29, 0
	v_lshl_add_u64 v[40:41], v[8:9], 0, s[28:29]
	global_load_dword v89, v[40:41], off
	s_add_u32 s28, s28, 0x3000
	s_addc_u32 s29, s29, 0
	v_lshl_add_u64 v[40:41], v[8:9], 0, s[28:29]
	global_load_dword v90, v[40:41], off
	s_add_u32 s28, s28, 0x3000
	s_addc_u32 s29, s29, 0
	v_lshl_add_u64 v[40:41], v[8:9], 0, s[28:29]
	global_load_dword v91, v[40:41], off
	s_add_u32 s28, s28, 0x3000
	s_addc_u32 s29, s29, 0
	v_lshl_add_u64 v[40:41], v[8:9], 0, s[28:29]
	global_load_dword v92, v[40:41], off
	s_add_u32 s28, s28, 0x3000
	s_addc_u32 s29, s29, 0
	v_lshl_add_u64 v[40:41], v[8:9], 0, s[28:29]
	global_load_dword v93, v[40:41], off
	s_add_u32 s28, s28, 0x3000
	s_addc_u32 s29, s29, 0
	v_lshl_add_u64 v[40:41], v[8:9], 0, s[28:29]
	global_load_dword v94, v[40:41], off
	s_add_u32 s28, s28, 0x3000
	s_addc_u32 s29, s29, 0
	v_lshl_add_u64 v[40:41], v[8:9], 0, s[28:29]
	global_load_dword v95, v[40:41], off
	s_add_u32 s28, s28, 0x3000
	s_addc_u32 s29, s29, 0
	v_lshl_add_u64 v[40:41], v[8:9], 0, s[28:29]
	global_load_dword v96, v[40:41], off
	s_add_u32 s28, s28, 0x3000
	s_addc_u32 s29, s29, 0
	v_lshl_add_u64 v[40:41], v[8:9], 0, s[28:29]
	global_load_dword v97, v[40:41], off
	s_add_u32 s28, s28, 0x3000
	s_addc_u32 s29, s29, 0
	v_lshl_add_u64 v[40:41], v[8:9], 0, s[28:29]
	global_load_dword v98, v[40:41], off
	s_add_u32 s28, s28, 0x3000
	s_addc_u32 s29, s29, 0
	v_lshl_add_u64 v[40:41], v[8:9], 0, s[28:29]
	global_load_dword v99, v[40:41], off
	s_add_u32 s28, s28, 0x3000
	s_addc_u32 s29, s29, 0
	v_lshl_add_u64 v[40:41], v[8:9], 0, s[28:29]
	global_load_dword v100, v[40:41], off
	s_add_u32 s28, s28, 0x3000
	s_addc_u32 s29, s29, 0
	v_lshl_add_u64 v[40:41], v[8:9], 0, s[28:29]
	global_load_dword v101, v[40:41], off
	s_add_u32 s28, s28, 0x3000
	s_addc_u32 s29, s29, 0
	v_lshl_add_u64 v[40:41], v[8:9], 0, s[28:29]
	global_load_dword v102, v[40:41], off
	s_add_u32 s28, s28, 0x3000
	s_addc_u32 s29, s29, 0
	v_lshl_add_u64 v[40:41], v[8:9], 0, s[28:29]
	global_load_dword v103, v[40:41], off
	s_add_u32 s28, s28, 0x3000
	s_addc_u32 s29, s29, 0
	v_lshl_add_u64 v[40:41], v[8:9], 0, s[28:29]
	global_load_dword v104, v[40:41], off
	s_add_u32 s28, s28, 0x3000
	s_addc_u32 s29, s29, 0
	v_lshl_add_u64 v[40:41], v[8:9], 0, s[28:29]
	global_load_dword v105, v[40:41], off
	s_add_u32 s28, s28, 0x3000
	s_addc_u32 s29, s29, 0
	v_lshl_add_u64 v[40:41], v[8:9], 0, s[28:29]
	global_load_dword v106, v[40:41], off
	s_add_u32 s28, s28, 0x3000
	s_addc_u32 s29, s29, 0
	v_lshl_add_u64 v[40:41], v[8:9], 0, s[28:29]
	global_load_dword v107, v[40:41], off
	s_add_u32 s28, s28, 0x3000
	s_addc_u32 s29, s29, 0
	v_lshl_add_u64 v[40:41], v[8:9], 0, s[28:29]
	global_load_dword v108, v[40:41], off
	s_add_u32 s28, s28, 0x3000
	s_addc_u32 s29, s29, 0
	v_lshl_add_u64 v[40:41], v[8:9], 0, s[28:29]
	global_load_dword v109, v[40:41], off
	s_add_u32 s28, s28, 0x3000
	s_addc_u32 s29, s29, 0
	v_lshl_add_u64 v[40:41], v[8:9], 0, s[28:29]
	global_load_dword v110, v[40:41], off
	s_add_u32 s28, s28, 0x3000
	s_addc_u32 s29, s29, 0
	v_lshl_add_u64 v[40:41], v[8:9], 0, s[28:29]
	global_load_dword v111, v[40:41], off
	s_add_u32 s28, s28, 0x3000
	s_addc_u32 s29, s29, 0
	v_lshl_add_u64 v[40:41], v[8:9], 0, s[28:29]
	global_load_dword v112, v[40:41], off
	s_add_u32 s28, s28, 0x3000
	s_addc_u32 s29, s29, 0
	v_lshl_add_u64 v[40:41], v[8:9], 0, s[28:29]
	global_load_dword v113, v[40:41], off
	s_add_u32 s28, s28, 0x3000
	s_addc_u32 s29, s29, 0
	v_lshl_add_u64 v[40:41], v[8:9], 0, s[28:29]
	global_load_dword v114, v[40:41], off
	s_add_u32 s28, s28, 0x3000
	s_addc_u32 s29, s29, 0
	v_lshl_add_u64 v[40:41], v[8:9], 0, s[28:29]
	global_load_dword v115, v[40:41], off
	s_add_u32 s28, s28, 0x3000
	s_addc_u32 s29, s29, 0
	v_lshl_add_u64 v[40:41], v[8:9], 0, s[28:29]
	global_load_dword v116, v[40:41], off
	s_add_u32 s28, s28, 0x3000
	s_addc_u32 s29, s29, 0
	v_lshl_add_u64 v[40:41], v[8:9], 0, s[28:29]
	global_load_dword v117, v[40:41], off
	s_add_u32 s28, s28, 0x3000
	s_addc_u32 s29, s29, 0
	v_lshl_add_u64 v[40:41], v[8:9], 0, s[28:29]
	global_load_dword v118, v[40:41], off
	s_add_u32 s28, s28, 0x3000
	s_addc_u32 s29, s29, 0
	v_lshl_add_u64 v[40:41], v[8:9], 0, s[28:29]
	global_load_dword v119, v[40:41], off
	s_add_u32 s28, s28, 0x3000
	s_addc_u32 s29, s29, 0
	ds_read_b128 v[14:17], v13
	ds_read_b128 v[18:21], v13 offset:16
	ds_read_b128 v[22:25], v13 offset:4096
	ds_read_b128 v[26:29], v13 offset:4112
	ds_read_b128 v[30:33], v13 offset:8192
	ds_read_b128 v[34:37], v13 offset:8208
	v_add_u32_e32 v13, 32, v13
	s_waitcnt lgkmcnt(0)
	s_waitcnt vmcnt(63)
	v_fmac_f32_e32 v10, v56, v14
	v_fmac_f32_e32 v11, v56, v22
	v_fmac_f32_e32 v12, v56, v30
	s_waitcnt vmcnt(62)
	v_fmac_f32_e32 v10, v57, v15
	v_fmac_f32_e32 v11, v57, v23
	v_fmac_f32_e32 v12, v57, v31
	s_waitcnt vmcnt(61)
	v_fmac_f32_e32 v10, v58, v16
	v_fmac_f32_e32 v11, v58, v24
	v_fmac_f32_e32 v12, v58, v32
	s_waitcnt vmcnt(60)
	v_fmac_f32_e32 v10, v59, v17
	v_fmac_f32_e32 v11, v59, v25
	v_fmac_f32_e32 v12, v59, v33
	s_waitcnt vmcnt(59)
	v_fmac_f32_e32 v10, v60, v18
	v_fmac_f32_e32 v11, v60, v26
	v_fmac_f32_e32 v12, v60, v34
	s_waitcnt vmcnt(58)
	v_fmac_f32_e32 v10, v61, v19
	v_fmac_f32_e32 v11, v61, v27
	v_fmac_f32_e32 v12, v61, v35
	s_waitcnt vmcnt(57)
	v_fmac_f32_e32 v10, v62, v20
	v_fmac_f32_e32 v11, v62, v28
	v_fmac_f32_e32 v12, v62, v36
	s_waitcnt vmcnt(56)
	v_fmac_f32_e32 v10, v63, v21
	v_fmac_f32_e32 v11, v63, v29
	v_fmac_f32_e32 v12, v63, v37
	ds_read_b128 v[14:17], v13
	ds_read_b128 v[18:21], v13 offset:16
	ds_read_b128 v[22:25], v13 offset:4096
	ds_read_b128 v[26:29], v13 offset:4112
	ds_read_b128 v[30:33], v13 offset:8192
	ds_read_b128 v[34:37], v13 offset:8208
	v_add_u32_e32 v13, 32, v13
	s_waitcnt lgkmcnt(0)
	s_waitcnt vmcnt(55)
	v_fmac_f32_e32 v10, v64, v14
	v_fmac_f32_e32 v11, v64, v22
	v_fmac_f32_e32 v12, v64, v30
	s_waitcnt vmcnt(54)
	v_fmac_f32_e32 v10, v65, v15
	v_fmac_f32_e32 v11, v65, v23
	v_fmac_f32_e32 v12, v65, v31
	s_waitcnt vmcnt(53)
	v_fmac_f32_e32 v10, v66, v16
	v_fmac_f32_e32 v11, v66, v24
	v_fmac_f32_e32 v12, v66, v32
	s_waitcnt vmcnt(52)
	v_fmac_f32_e32 v10, v67, v17
	v_fmac_f32_e32 v11, v67, v25
	v_fmac_f32_e32 v12, v67, v33
	s_waitcnt vmcnt(51)
	v_fmac_f32_e32 v10, v68, v18
	v_fmac_f32_e32 v11, v68, v26
	v_fmac_f32_e32 v12, v68, v34
	s_waitcnt vmcnt(50)
	v_fmac_f32_e32 v10, v69, v19
	v_fmac_f32_e32 v11, v69, v27
	v_fmac_f32_e32 v12, v69, v35
	s_waitcnt vmcnt(49)
	v_fmac_f32_e32 v10, v70, v20
	v_fmac_f32_e32 v11, v70, v28
	v_fmac_f32_e32 v12, v70, v36
	s_waitcnt vmcnt(48)
	v_fmac_f32_e32 v10, v71, v21
	v_fmac_f32_e32 v11, v71, v29
	v_fmac_f32_e32 v12, v71, v37
	ds_read_b128 v[14:17], v13
	ds_read_b128 v[18:21], v13 offset:16
	ds_read_b128 v[22:25], v13 offset:4096
	ds_read_b128 v[26:29], v13 offset:4112
	ds_read_b128 v[30:33], v13 offset:8192
	ds_read_b128 v[34:37], v13 offset:8208
	v_add_u32_e32 v13, 32, v13
	s_waitcnt lgkmcnt(0)
	s_waitcnt vmcnt(47)
	v_fmac_f32_e32 v10, v72, v14
	v_fmac_f32_e32 v11, v72, v22
	v_fmac_f32_e32 v12, v72, v30
	s_waitcnt vmcnt(46)
	v_fmac_f32_e32 v10, v73, v15
	v_fmac_f32_e32 v11, v73, v23
	v_fmac_f32_e32 v12, v73, v31
	s_waitcnt vmcnt(45)
	v_fmac_f32_e32 v10, v74, v16
	v_fmac_f32_e32 v11, v74, v24
	v_fmac_f32_e32 v12, v74, v32
	s_waitcnt vmcnt(44)
	v_fmac_f32_e32 v10, v75, v17
	v_fmac_f32_e32 v11, v75, v25
	v_fmac_f32_e32 v12, v75, v33
	s_waitcnt vmcnt(43)
	v_fmac_f32_e32 v10, v76, v18
	v_fmac_f32_e32 v11, v76, v26
	v_fmac_f32_e32 v12, v76, v34
	s_waitcnt vmcnt(42)
	v_fmac_f32_e32 v10, v77, v19
	v_fmac_f32_e32 v11, v77, v27
	v_fmac_f32_e32 v12, v77, v35
	s_waitcnt vmcnt(41)
	v_fmac_f32_e32 v10, v78, v20
	v_fmac_f32_e32 v11, v78, v28
	v_fmac_f32_e32 v12, v78, v36
	s_waitcnt vmcnt(40)
	v_fmac_f32_e32 v10, v79, v21
	v_fmac_f32_e32 v11, v79, v29
	v_fmac_f32_e32 v12, v79, v37
	ds_read_b128 v[14:17], v13
	ds_read_b128 v[18:21], v13 offset:16
	ds_read_b128 v[22:25], v13 offset:4096
	ds_read_b128 v[26:29], v13 offset:4112
	ds_read_b128 v[30:33], v13 offset:8192
	ds_read_b128 v[34:37], v13 offset:8208
	v_add_u32_e32 v13, 32, v13
	s_waitcnt lgkmcnt(0)
	s_waitcnt vmcnt(39)
	v_fmac_f32_e32 v10, v80, v14
	v_fmac_f32_e32 v11, v80, v22
	v_fmac_f32_e32 v12, v80, v30
	s_waitcnt vmcnt(38)
	v_fmac_f32_e32 v10, v81, v15
	v_fmac_f32_e32 v11, v81, v23
	v_fmac_f32_e32 v12, v81, v31
	s_waitcnt vmcnt(37)
	v_fmac_f32_e32 v10, v82, v16
	v_fmac_f32_e32 v11, v82, v24
	v_fmac_f32_e32 v12, v82, v32
	s_waitcnt vmcnt(36)
	v_fmac_f32_e32 v10, v83, v17
	v_fmac_f32_e32 v11, v83, v25
	v_fmac_f32_e32 v12, v83, v33
	s_waitcnt vmcnt(35)
	v_fmac_f32_e32 v10, v84, v18
	v_fmac_f32_e32 v11, v84, v26
	v_fmac_f32_e32 v12, v84, v34
	s_waitcnt vmcnt(34)
	v_fmac_f32_e32 v10, v85, v19
	v_fmac_f32_e32 v11, v85, v27
	v_fmac_f32_e32 v12, v85, v35
	s_waitcnt vmcnt(33)
	v_fmac_f32_e32 v10, v86, v20
	v_fmac_f32_e32 v11, v86, v28
	v_fmac_f32_e32 v12, v86, v36
	s_waitcnt vmcnt(32)
	v_fmac_f32_e32 v10, v87, v21
	v_fmac_f32_e32 v11, v87, v29
	v_fmac_f32_e32 v12, v87, v37
	ds_read_b128 v[14:17], v13
	ds_read_b128 v[18:21], v13 offset:16
	ds_read_b128 v[22:25], v13 offset:4096
	ds_read_b128 v[26:29], v13 offset:4112
	ds_read_b128 v[30:33], v13 offset:8192
	ds_read_b128 v[34:37], v13 offset:8208
	v_add_u32_e32 v13, 32, v13
	s_waitcnt lgkmcnt(0)
	s_waitcnt vmcnt(31)
	v_fmac_f32_e32 v10, v88, v14
	v_fmac_f32_e32 v11, v88, v22
	v_fmac_f32_e32 v12, v88, v30
	s_waitcnt vmcnt(30)
	v_fmac_f32_e32 v10, v89, v15
	v_fmac_f32_e32 v11, v89, v23
	v_fmac_f32_e32 v12, v89, v31
	s_waitcnt vmcnt(29)
	v_fmac_f32_e32 v10, v90, v16
	v_fmac_f32_e32 v11, v90, v24
	v_fmac_f32_e32 v12, v90, v32
	s_waitcnt vmcnt(28)
	v_fmac_f32_e32 v10, v91, v17
	v_fmac_f32_e32 v11, v91, v25
	v_fmac_f32_e32 v12, v91, v33
	s_waitcnt vmcnt(27)
	v_fmac_f32_e32 v10, v92, v18
	v_fmac_f32_e32 v11, v92, v26
	v_fmac_f32_e32 v12, v92, v34
	s_waitcnt vmcnt(26)
	v_fmac_f32_e32 v10, v93, v19
	v_fmac_f32_e32 v11, v93, v27
	v_fmac_f32_e32 v12, v93, v35
	s_waitcnt vmcnt(25)
	v_fmac_f32_e32 v10, v94, v20
	v_fmac_f32_e32 v11, v94, v28
	v_fmac_f32_e32 v12, v94, v36
	s_waitcnt vmcnt(24)
	v_fmac_f32_e32 v10, v95, v21
	v_fmac_f32_e32 v11, v95, v29
	v_fmac_f32_e32 v12, v95, v37
	ds_read_b128 v[14:17], v13
	ds_read_b128 v[18:21], v13 offset:16
	ds_read_b128 v[22:25], v13 offset:4096
	ds_read_b128 v[26:29], v13 offset:4112
	ds_read_b128 v[30:33], v13 offset:8192
	ds_read_b128 v[34:37], v13 offset:8208
	v_add_u32_e32 v13, 32, v13
	s_waitcnt lgkmcnt(0)
	s_waitcnt vmcnt(23)
	v_fmac_f32_e32 v10, v96, v14
	v_fmac_f32_e32 v11, v96, v22
	v_fmac_f32_e32 v12, v96, v30
	s_waitcnt vmcnt(22)
	v_fmac_f32_e32 v10, v97, v15
	v_fmac_f32_e32 v11, v97, v23
	v_fmac_f32_e32 v12, v97, v31
	s_waitcnt vmcnt(21)
	v_fmac_f32_e32 v10, v98, v16
	v_fmac_f32_e32 v11, v98, v24
	v_fmac_f32_e32 v12, v98, v32
	s_waitcnt vmcnt(20)
	v_fmac_f32_e32 v10, v99, v17
	v_fmac_f32_e32 v11, v99, v25
	v_fmac_f32_e32 v12, v99, v33
	s_waitcnt vmcnt(19)
	v_fmac_f32_e32 v10, v100, v18
	v_fmac_f32_e32 v11, v100, v26
	v_fmac_f32_e32 v12, v100, v34
	s_waitcnt vmcnt(18)
	v_fmac_f32_e32 v10, v101, v19
	v_fmac_f32_e32 v11, v101, v27
	v_fmac_f32_e32 v12, v101, v35
	s_waitcnt vmcnt(17)
	v_fmac_f32_e32 v10, v102, v20
	v_fmac_f32_e32 v11, v102, v28
	v_fmac_f32_e32 v12, v102, v36
	s_waitcnt vmcnt(16)
	v_fmac_f32_e32 v10, v103, v21
	v_fmac_f32_e32 v11, v103, v29
	v_fmac_f32_e32 v12, v103, v37
	ds_read_b128 v[14:17], v13
	ds_read_b128 v[18:21], v13 offset:16
	ds_read_b128 v[22:25], v13 offset:4096
	ds_read_b128 v[26:29], v13 offset:4112
	ds_read_b128 v[30:33], v13 offset:8192
	ds_read_b128 v[34:37], v13 offset:8208
	v_add_u32_e32 v13, 32, v13
	s_waitcnt lgkmcnt(0)
	s_waitcnt vmcnt(15)
	v_fmac_f32_e32 v10, v104, v14
	v_fmac_f32_e32 v11, v104, v22
	v_fmac_f32_e32 v12, v104, v30
	s_waitcnt vmcnt(14)
	v_fmac_f32_e32 v10, v105, v15
	v_fmac_f32_e32 v11, v105, v23
	v_fmac_f32_e32 v12, v105, v31
	s_waitcnt vmcnt(13)
	v_fmac_f32_e32 v10, v106, v16
	v_fmac_f32_e32 v11, v106, v24
	v_fmac_f32_e32 v12, v106, v32
	s_waitcnt vmcnt(12)
	v_fmac_f32_e32 v10, v107, v17
	v_fmac_f32_e32 v11, v107, v25
	v_fmac_f32_e32 v12, v107, v33
	s_waitcnt vmcnt(11)
	v_fmac_f32_e32 v10, v108, v18
	v_fmac_f32_e32 v11, v108, v26
	v_fmac_f32_e32 v12, v108, v34
	s_waitcnt vmcnt(10)
	v_fmac_f32_e32 v10, v109, v19
	v_fmac_f32_e32 v11, v109, v27
	v_fmac_f32_e32 v12, v109, v35
	s_waitcnt vmcnt(9)
	v_fmac_f32_e32 v10, v110, v20
	v_fmac_f32_e32 v11, v110, v28
	v_fmac_f32_e32 v12, v110, v36
	s_waitcnt vmcnt(8)
	v_fmac_f32_e32 v10, v111, v21
	v_fmac_f32_e32 v11, v111, v29
	v_fmac_f32_e32 v12, v111, v37
	ds_read_b128 v[14:17], v13
	ds_read_b128 v[18:21], v13 offset:16
	ds_read_b128 v[22:25], v13 offset:4096
	ds_read_b128 v[26:29], v13 offset:4112
	ds_read_b128 v[30:33], v13 offset:8192
	ds_read_b128 v[34:37], v13 offset:8208
	v_add_u32_e32 v13, 32, v13
	s_waitcnt lgkmcnt(0)
	s_waitcnt vmcnt(7)
	v_fmac_f32_e32 v10, v112, v14
	v_fmac_f32_e32 v11, v112, v22
	v_fmac_f32_e32 v12, v112, v30
	s_waitcnt vmcnt(6)
	v_fmac_f32_e32 v10, v113, v15
	v_fmac_f32_e32 v11, v113, v23
	v_fmac_f32_e32 v12, v113, v31
	s_waitcnt vmcnt(5)
	v_fmac_f32_e32 v10, v114, v16
	v_fmac_f32_e32 v11, v114, v24
	v_fmac_f32_e32 v12, v114, v32
	s_waitcnt vmcnt(4)
	v_fmac_f32_e32 v10, v115, v17
	v_fmac_f32_e32 v11, v115, v25
	v_fmac_f32_e32 v12, v115, v33
	s_waitcnt vmcnt(3)
	v_fmac_f32_e32 v10, v116, v18
	v_fmac_f32_e32 v11, v116, v26
	v_fmac_f32_e32 v12, v116, v34
	s_waitcnt vmcnt(2)
	v_fmac_f32_e32 v10, v117, v19
	v_fmac_f32_e32 v11, v117, v27
	v_fmac_f32_e32 v12, v117, v35
	s_waitcnt vmcnt(1)
	v_fmac_f32_e32 v10, v118, v20
	v_fmac_f32_e32 v11, v118, v28
	v_fmac_f32_e32 v12, v118, v36
	s_waitcnt vmcnt(0)
	v_fmac_f32_e32 v10, v119, v21
	v_fmac_f32_e32 v11, v119, v29
	v_fmac_f32_e32 v12, v119, v37
	s_cmp_eq_u32 s28, 0x180000
	s_cbranch_scc0 .LBB0_6
	ds_write2st64_b32 v3, v10, v11 offset0:48 offset1:49
	ds_write_b32 v3, v12 offset:12800
	s_waitcnt lgkmcnt(0)
	s_barrier
	s_and_saveexec_b64 s[4:5], vcc
	s_cbranch_execz .LBB0_4
	s_load_dwordx16 s[36:51], s[0:1], 0x40
	s_mul_i32 s13, s22, 0xc00
	s_add_i32 s13, s13, s12
	v_or_b32_e32 v8, s13, v2
	v_ashrrev_i32_e32 v9, 31, v8
	s_waitcnt lgkmcnt(0)
	v_lshl_add_u64 v[8:9], v[8:9], 2, s[40:41]
	global_load_dword v18, v[8:9], off
	ds_read2st64_b32 v[8:9], v7 offset0:48 offset1:51
	ds_read2st64_b32 v[10:11], v7 offset0:54 offset1:57
	ds_read2st64_b32 v[12:13], v7 offset0:60 offset1:63
	ds_read2st64_b32 v[14:15], v7 offset0:66 offset1:69
	v_mad_u64_u32 v[16:17], s[22:23], s22, 3, v[6:7]
	v_mul_lo_u32 v16, v16, s20
	v_add_u32_e32 v16, s12, v16
	v_or_b32_e32 v16, v16, v2
	v_ashrrev_i32_e32 v17, 31, v16
	s_waitcnt vmcnt(0) lgkmcnt(3)
	v_add_f32_e32 v8, v18, v8
	v_add_f32_e32 v8, v8, v9
	s_waitcnt lgkmcnt(2)
	v_add_f32_e32 v8, v8, v10
	v_add_f32_e32 v8, v8, v11
	s_waitcnt lgkmcnt(1)
	v_add_f32_e32 v8, v8, v12
	v_add_f32_e32 v8, v8, v13
	s_waitcnt lgkmcnt(0)
	v_add_f32_e32 v8, v8, v14
	v_add_f32_e32 v10, v8, v15
	v_lshl_add_u64 v[8:9], v[16:17], 2, s[10:11]
	global_store_dword v[8:9], v10, off
	s_branch .LBB0_4
